# diff_unit4 (pipelined unit actually taken) epilogue: xor butterflies 1,2,4,8 via DPP instead of ds_swizzle
# baseline (speedup 1.0000x reference)
.LBB0_1402:
	s_waitcnt lgkmcnt(0)
	s_barrier
	s_cmpk_gt_u32 s73, 0xff
	s_cbranch_scc1 .LBB0_1312
	v_readlane_b32 s0, v255, 14
	v_readlane_b32 s1, v255, 15
	s_nop 4
	global_load_dword v29, v15, s[0:1]
	global_load_dword v43, v15, s[0:1] offset:128
	global_load_dword v48, v15, s[0:1] offset:256
	global_load_dword v49, v15, s[0:1] offset:384
	s_lshl_b32 s0, s72, 13
	s_lshl_b32 s1, s72, 14
	s_add_i32 s0, s0, 0
	s_add_i32 s1, s1, 0
	v_lshlrev_b32_e32 v16, 10, v94
	v_lshlrev_b32_e32 v17, 1, v95
	s_add_i32 s0, s0, 0x10000
	v_add3_u32 v15, s1, v6, v15
	v_add3_u32 v6, s0, v16, v17
	ds_read2_b32 v[16:17], v15 offset1:32
	ds_read2_b32 v[22:23], v15 offset0:64 offset1:96
	ds_read2_b32 v[30:31], v15 offset0:128 offset1:160
	ds_read2_b32 v[32:33], v15 offset0:192 offset1:224
	v_add_u32_e32 v57, 0x400, v15
	s_waitcnt lgkmcnt(3)
	v_sub_f32_e32 v17, v85, v17
	v_sub_f32_e32 v16, v83, v16
	v_mul_f32_e32 v58, v17, v17
	s_waitcnt lgkmcnt(2)
	v_sub_f32_e32 v22, v86, v22
	v_fmac_f32_e32 v58, v16, v16
	v_sub_f32_e32 v23, v87, v23
	v_fmac_f32_e32 v58, v22, v22
	v_fmac_f32_e32 v58, v23, v23
	s_nop 1
	v_mov_b32_dpp v59, v58 quad_perm:[1,0,3,2] row_mask:0xf bank_mask:0xf
	s_waitcnt lgkmcnt(1)
	v_sub_f32_e32 v31, v92, v31
	v_sub_f32_e32 v30, v90, v30
	v_mul_f32_e32 v60, v31, v31
	s_waitcnt lgkmcnt(0)
	v_sub_f32_e32 v32, v93, v32
	v_add_f32_e32 v58, v58, v59
	s_nop 1
	v_mov_b32_dpp v59, v58 quad_perm:[2,3,0,1] row_mask:0xf bank_mask:0xf
	v_fmac_f32_e32 v60, v30, v30
	v_sub_f32_e32 v33, v88, v33
	v_fmac_f32_e32 v60, v32, v32
	v_fmac_f32_e32 v60, v33, v33
	v_add_f32_e32 v58, v58, v59
	s_nop 0
	v_mov_b32_dpp v61, v60 quad_perm:[1,0,3,2] row_mask:0xf bank_mask:0xf
	v_mov_b32_dpp v59, v58 row_half_mirror row_mask:0xf bank_mask:0xf
	ds_read2_b32 v[44:45], v57 offset1:32
	ds_read2_b32 v[46:47], v57 offset0:64 offset1:96
	s_lshl_b64 s[4:5], s[60:61], 11
	s_add_u32 s1, s91, s4
	v_add_f32_e32 v60, v60, v61
	v_add_f32_e32 v58, v58, v59
	s_nop 0
	v_mov_b32_dpp v61, v60 quad_perm:[2,3,0,1] row_mask:0xf bank_mask:0xf
	v_mov_b32_dpp v59, v58 row_mirror row_mask:0xf bank_mask:0xf
	s_waitcnt lgkmcnt(1)
	v_sub_f32_e32 v45, v91, v45
	v_sub_f32_e32 v44, v89, v44
	v_mul_f32_e32 v62, v45, v45
	v_add_f32_e32 v60, v60, v61
	v_add_f32_e32 v58, v58, v59
	s_nop 0
	v_mov_b32_dpp v61, v60 row_half_mirror row_mask:0xf bank_mask:0xf
	ds_swizzle_b32 v59, v58 offset:swizzle(SWAP,16)
	s_waitcnt lgkmcnt(1)
	v_sub_f32_e32 v46, v84, v46
	v_fmac_f32_e32 v62, v44, v44
	v_sub_f32_e32 v47, v82, v47
	v_add_f32_e32 v60, v60, v61
	s_waitcnt lgkmcnt(0)
	v_add_f32_e32 v58, v58, v59
	v_mov_b32_dpp v61, v60 row_mirror row_mask:0xf bank_mask:0xf
	v_fmamk_f32 v58, v58, 0x3c000000, v244
	v_fmac_f32_e32 v62, v46, v46
	v_rsq_f32_e32 v58, v58
	v_fmac_f32_e32 v62, v47, v47
	s_nop 1
	v_mov_b32_dpp v59, v62 quad_perm:[1,0,3,2] row_mask:0xf bank_mask:0xf
	v_add_f32_e32 v60, v60, v61
	v_mul_f32_e32 v63, v16, v58
	v_mul_f32_e32 v64, v17, v58
	v_mul_f32_e32 v65, v22, v58
	v_mul_f32_e32 v58, v23, v58
	ds_swizzle_b32 v61, v60 offset:swizzle(SWAP,16)
	s_addc_u32 s5, s95, s5
	s_add_u32 s4, s1, s8
	s_addc_u32 s5, s5, 0
	s_waitcnt vmcnt(3)
	v_mul_f32_e32 v23, 0x3f4ccccd, v29
	s_waitcnt vmcnt(2)
	v_mul_f32_e32 v22, 0x3f4ccccd, v43
	s_waitcnt vmcnt(1)
	v_mul_f32_e32 v17, 0x3f4ccccd, v48
	v_mul_f32_e32 v29, v23, v63
	v_mul_f32_e32 v43, v22, v64
	v_mul_f32_e32 v48, v17, v65
	v_cvt_pk_bf16_f32 v29, v29, s0
	v_cvt_pk_bf16_f32 v43, v43, s0
	v_cvt_pk_bf16_f32 v48, v48, s0
	ds_write_b16 v6, v29
	ds_write_b16 v6, v43 offset:64
	ds_write_b16 v6, v48 offset:128
	v_add_f32_e32 v43, v62, v59
	s_nop 1
	v_mov_b32_dpp v48, v43 quad_perm:[2,3,0,1] row_mask:0xf bank_mask:0xf
	s_waitcnt lgkmcnt(3)
	v_add_f32_e32 v29, v60, v61
	v_fmamk_f32 v29, v29, 0x3c000000, v244
	v_rsq_f32_e32 v29, v29
	s_waitcnt vmcnt(0)
	v_mul_f32_e32 v16, 0x3f4ccccd, v49
	v_add_f32_e32 v43, v43, v48
	s_nop 1
	v_mov_b32_dpp v48, v43 row_half_mirror row_mask:0xf bank_mask:0xf
	v_mul_f32_e32 v30, v30, v29
	v_mul_f32_e32 v30, v23, v30
	v_cvt_pk_bf16_f32 v30, v30, s0
	ds_write_b16 v6, v30 offset:256
	v_mul_f32_e32 v30, v31, v29
	v_add_f32_e32 v31, v43, v48
	s_nop 1
	v_mov_b32_dpp v43, v31 row_mirror row_mask:0xf bank_mask:0xf
	v_mul_f32_e32 v30, v22, v30
	v_cvt_pk_bf16_f32 v30, v30, s0
	ds_write_b16 v6, v30 offset:320
	v_mul_f32_e32 v30, v32, v29
	v_add_f32_e32 v31, v31, v43
	ds_swizzle_b32 v32, v31 offset:swizzle(SWAP,16)
	v_mul_f32_e32 v30, v17, v30
	v_cvt_pk_bf16_f32 v30, v30, s0
	ds_write_b16 v6, v30 offset:384
	v_mul_f32_e32 v29, v33, v29
	s_waitcnt lgkmcnt(1)
	v_add_f32_e32 v30, v31, v32
	v_fmamk_f32 v30, v30, 0x3c000000, v244
	v_rsq_f32_e32 v43, v30
	ds_read2_b32 v[30:31], v57 offset0:128 offset1:160
	ds_read2_b32 v[32:33], v57 offset0:192 offset1:224
	v_mul_f32_e32 v29, v16, v29
	v_mul_f32_e32 v49, v16, v58
	v_cvt_pk_bf16_f32 v29, v29, s0
	s_waitcnt lgkmcnt(1)
	v_sub_f32_e32 v48, v81, v31
	v_cvt_pk_bf16_f32 v49, v49, s0
	ds_write_b16 v6, v29 offset:448
	v_mul_f32_e32 v29, v44, v43
	v_sub_f32_e32 v44, v78, v30
	v_mul_f32_e32 v30, v48, v48
	ds_write_b16 v6, v49 offset:192
	v_fmac_f32_e32 v30, v44, v44
	s_waitcnt lgkmcnt(2)
	v_sub_f32_e32 v49, v80, v32
	v_fmac_f32_e32 v30, v49, v49
	v_sub_f32_e32 v57, v79, v33
	v_fmac_f32_e32 v30, v57, v57
	s_nop 1
	v_mov_b32_dpp v31, v30 quad_perm:[1,0,3,2] row_mask:0xf bank_mask:0xf
	v_mul_f32_e32 v29, v23, v29
	v_cvt_pk_bf16_f32 v29, v29, s0
	ds_write_b16 v6, v29 offset:512
	v_mul_f32_e32 v29, v45, v43
	v_add_f32_e32 v30, v30, v31
	s_nop 1
	v_mov_b32_dpp v31, v30 quad_perm:[2,3,0,1] row_mask:0xf bank_mask:0xf
	v_mul_f32_e32 v29, v22, v29
	v_cvt_pk_bf16_f32 v29, v29, s0
	ds_write_b16 v6, v29 offset:576
	v_mul_f32_e32 v29, v46, v43
	v_add_f32_e32 v30, v30, v31
	s_nop 1
	v_mov_b32_dpp v31, v30 row_half_mirror row_mask:0xf bank_mask:0xf
	v_mul_f32_e32 v29, v17, v29
	v_cvt_pk_bf16_f32 v29, v29, s0
	ds_write_b16 v6, v29 offset:640
	v_mul_f32_e32 v29, v47, v43
	v_add_f32_e32 v32, v30, v31
	s_nop 1
	v_mov_b32_dpp v33, v32 row_mirror row_mask:0xf bank_mask:0xf
	v_add_u32_e32 v43, 0x1000, v15
	ds_read2_b32 v[30:31], v43 offset1:32
	v_mul_f32_e32 v29, v16, v29
	v_cvt_pk_bf16_f32 v29, v29, s0
	v_add_f32_e32 v45, v32, v33
	ds_read2_b32 v[32:33], v43 offset0:64 offset1:96
	s_waitcnt lgkmcnt(1)
	v_sub_f32_e32 v58, v77, v31
	v_sub_f32_e32 v47, v74, v30
	v_mul_f32_e32 v30, v58, v58
	v_fmac_f32_e32 v30, v47, v47
	s_waitcnt lgkmcnt(0)
	v_sub_f32_e32 v59, v76, v32
	v_fmac_f32_e32 v30, v59, v59
	v_sub_f32_e32 v60, v75, v33
	v_fmac_f32_e32 v30, v60, v60
	s_nop 1
	v_mov_b32_dpp v31, v30 quad_perm:[1,0,3,2] row_mask:0xf bank_mask:0xf
	ds_write_b16 v6, v29 offset:704
	ds_swizzle_b32 v46, v45 offset:swizzle(SWAP,16)
	v_add_f32_e32 v29, v30, v31
	s_nop 1
	v_mov_b32_dpp v30, v29 quad_perm:[2,3,0,1] row_mask:0xf bank_mask:0xf
	s_waitcnt lgkmcnt(0)
	v_add_f32_e32 v32, v45, v46
	v_fmamk_f32 v32, v32, 0x3c000000, v244
	v_rsq_f32_e32 v32, v32
	v_add_f32_e32 v29, v29, v30
	s_nop 1
	v_mov_b32_dpp v30, v29 row_half_mirror row_mask:0xf bank_mask:0xf
	v_mul_f32_e32 v31, v44, v32
	v_mul_f32_e32 v31, v23, v31
	v_cvt_pk_bf16_f32 v31, v31, s0
	ds_write_b16 v6, v31 offset:768
	v_add_f32_e32 v29, v29, v30
	s_nop 1
	v_mov_b32_dpp v30, v29 row_mirror row_mask:0xf bank_mask:0xf
	v_mul_f32_e32 v31, v48, v32
	v_mul_f32_e32 v31, v22, v31
	v_cvt_pk_bf16_f32 v31, v31, s0
	ds_write_b16 v6, v31 offset:832
	v_add_f32_e32 v29, v29, v30
	v_mul_f32_e32 v31, v49, v32
	ds_swizzle_b32 v33, v29 offset:swizzle(SWAP,16)
	v_mul_f32_e32 v31, v17, v31
	v_mul_f32_e32 v30, v57, v32
	v_cvt_pk_bf16_f32 v31, v31, s0
	v_mul_f32_e32 v30, v16, v30
	ds_write_b16 v6, v31 offset:896
	v_cvt_pk_bf16_f32 v44, v30, s0
	ds_read2_b32 v[30:31], v43 offset0:128 offset1:160
	s_waitcnt lgkmcnt(2)
	v_add_f32_e32 v29, v29, v33
	ds_read2_b32 v[32:33], v43 offset0:192 offset1:224
	v_fmamk_f32 v29, v29, 0x3c000000, v244
	v_rsq_f32_e32 v29, v29
	s_waitcnt lgkmcnt(1)
	v_sub_f32_e32 v45, v73, v31
	v_sub_f32_e32 v43, v70, v30
	v_mul_f32_e32 v30, v45, v45
	v_fmac_f32_e32 v30, v43, v43
	s_waitcnt lgkmcnt(0)
	v_sub_f32_e32 v46, v72, v32
	v_fmac_f32_e32 v30, v46, v46
	v_sub_f32_e32 v48, v71, v33
	v_fmac_f32_e32 v30, v48, v48
	s_nop 1
	v_mov_b32_dpp v31, v30 quad_perm:[1,0,3,2] row_mask:0xf bank_mask:0xf
	v_mul_f32_e32 v32, v47, v29
	v_mul_f32_e32 v32, v23, v32
	v_cvt_pk_bf16_f32 v32, v32, s0
	ds_write_b16 v6, v32 offset:2048
	v_add_f32_e32 v30, v30, v31
	s_nop 1
	v_mov_b32_dpp v31, v30 quad_perm:[2,3,0,1] row_mask:0xf bank_mask:0xf
	v_mul_f32_e32 v32, v58, v29
	ds_write_b16 v6, v44 offset:960
	v_mul_f32_e32 v32, v22, v32
	v_cvt_pk_bf16_f32 v32, v32, s0
	v_add_f32_e32 v30, v30, v31
	s_nop 1
	v_mov_b32_dpp v31, v30 row_half_mirror row_mask:0xf bank_mask:0xf
	ds_write_b16 v6, v32 offset:2112
	v_mul_f32_e32 v32, v59, v29
	v_add_u32_e32 v47, 0x1400, v15
	v_mul_f32_e32 v32, v17, v32
	v_add_f32_e32 v33, v30, v31
	s_nop 1
	v_mov_b32_dpp v44, v33 row_mirror row_mask:0xf bank_mask:0xf
	ds_read2_b32 v[30:31], v47 offset1:32
	v_cvt_pk_bf16_f32 v32, v32, s0
	ds_write_b16 v6, v32 offset:2176
	v_mul_f32_e32 v29, v60, v29
	v_add_f32_e32 v44, v33, v44
	ds_read2_b32 v[32:33], v47 offset0:64 offset1:96
	s_waitcnt lgkmcnt(2)
	v_sub_f32_e32 v58, v68, v31
	v_sub_f32_e32 v57, v67, v30
	v_mul_f32_e32 v30, v58, v58
	v_fmac_f32_e32 v30, v57, v57
	s_waitcnt lgkmcnt(0)
	v_sub_f32_e32 v59, v69, v32
	v_fmac_f32_e32 v30, v59, v59
	v_sub_f32_e32 v56, v56, v33
	v_fmac_f32_e32 v30, v56, v56
	s_nop 1
	v_mov_b32_dpp v31, v30 quad_perm:[1,0,3,2] row_mask:0xf bank_mask:0xf
	ds_swizzle_b32 v49, v44 offset:swizzle(SWAP,16)
	v_mul_f32_e32 v29, v16, v29
	v_cvt_pk_bf16_f32 v29, v29, s0
	ds_write_b16 v6, v29 offset:2240
	v_add_f32_e32 v30, v30, v31
	s_nop 1
	v_mov_b32_dpp v31, v30 quad_perm:[2,3,0,1] row_mask:0xf bank_mask:0xf
	s_waitcnt lgkmcnt(1)
	v_add_f32_e32 v32, v44, v49
	v_fmamk_f32 v32, v32, 0x3c000000, v244
	v_rsq_f32_e32 v32, v32
	v_add_f32_e32 v30, v30, v31
	s_nop 1
	v_mov_b32_dpp v31, v30 row_half_mirror row_mask:0xf bank_mask:0xf
	v_mul_f32_e32 v29, v43, v32
	v_mul_f32_e32 v29, v23, v29
	v_cvt_pk_bf16_f32 v29, v29, s0
	ds_write_b16 v6, v29 offset:2304
	v_add_f32_e32 v30, v30, v31
	s_nop 1
	v_mov_b32_dpp v31, v30 row_mirror row_mask:0xf bank_mask:0xf
	v_mul_f32_e32 v29, v45, v32
	v_mul_f32_e32 v29, v22, v29
	v_cvt_pk_bf16_f32 v29, v29, s0
	ds_write_b16 v6, v29 offset:2368
	v_add_f32_e32 v30, v30, v31
	ds_swizzle_b32 v31, v30 offset:swizzle(SWAP,16)
	v_mul_f32_e32 v29, v46, v32
	v_mul_f32_e32 v29, v17, v29
	v_cvt_pk_bf16_f32 v29, v29, s0
	ds_write_b16 v6, v29 offset:2432
	s_waitcnt lgkmcnt(1)
	v_add_f32_e32 v30, v30, v31
	v_fmamk_f32 v30, v30, 0x3c000000, v244
	v_rsq_f32_e32 v43, v30
	ds_read2_b32 v[30:31], v47 offset0:128 offset1:160
	v_mul_f32_e32 v29, v48, v32
	ds_read2_b32 v[32:33], v47 offset0:192 offset1:224
	v_mul_f32_e32 v29, v16, v29
	v_cvt_pk_bf16_f32 v29, v29, s0
	s_waitcnt lgkmcnt(1)
	v_sub_f32_e32 v45, v55, v31
	v_sub_f32_e32 v44, v52, v30
	v_mul_f32_e32 v30, v45, v45
	v_fmac_f32_e32 v30, v44, v44
	s_waitcnt lgkmcnt(0)
	v_sub_f32_e32 v46, v54, v32
	v_fmac_f32_e32 v30, v46, v46
	v_sub_f32_e32 v47, v53, v33
	v_fmac_f32_e32 v30, v47, v47
	s_nop 1
	v_mov_b32_dpp v31, v30 quad_perm:[1,0,3,2] row_mask:0xf bank_mask:0xf
	ds_write_b16 v6, v29 offset:2496
	v_mul_f32_e32 v29, v57, v43
	v_mul_f32_e32 v29, v23, v29
	v_cvt_pk_bf16_f32 v29, v29, s0
	v_add_f32_e32 v30, v30, v31
	s_nop 1
	v_mov_b32_dpp v31, v30 quad_perm:[2,3,0,1] row_mask:0xf bank_mask:0xf
	ds_write_b16 v6, v29 offset:2560
	v_mul_f32_e32 v29, v58, v43
	v_mul_f32_e32 v29, v22, v29
	v_cvt_pk_bf16_f32 v29, v29, s0
	v_add_f32_e32 v30, v30, v31
	s_nop 1
	v_mov_b32_dpp v31, v30 row_half_mirror row_mask:0xf bank_mask:0xf
	ds_write_b16 v6, v29 offset:2624
	v_mul_f32_e32 v29, v59, v43
	v_mul_f32_e32 v29, v17, v29
	v_cvt_pk_bf16_f32 v29, v29, s0
	v_add_f32_e32 v32, v30, v31
	s_nop 1
	v_mov_b32_dpp v33, v32 row_mirror row_mask:0xf bank_mask:0xf
	ds_write_b16 v6, v29 offset:2688
	v_mul_f32_e32 v29, v56, v43
	v_add_u32_e32 v43, 0x2000, v15
	ds_read2_b32 v[30:31], v43 offset1:32
	v_add_f32_e32 v48, v32, v33
	ds_read2_b32 v[32:33], v43 offset0:64 offset1:96
	v_mul_f32_e32 v29, v16, v29
	v_cvt_pk_bf16_f32 v29, v29, s0
	s_waitcnt lgkmcnt(1)
	v_sub_f32_e32 v51, v51, v31
	v_sub_f32_e32 v50, v50, v30
	v_mul_f32_e32 v30, v51, v51
	v_fmac_f32_e32 v30, v50, v50
	s_waitcnt lgkmcnt(0)
	v_sub_f32_e32 v42, v42, v32
	v_fmac_f32_e32 v30, v42, v42
	v_sub_f32_e32 v41, v41, v33
	v_fmac_f32_e32 v30, v41, v41
	s_nop 1
	v_mov_b32_dpp v31, v30 quad_perm:[1,0,3,2] row_mask:0xf bank_mask:0xf
	ds_write_b16 v6, v29 offset:2752
	ds_swizzle_b32 v49, v48 offset:swizzle(SWAP,16)
	v_add_f32_e32 v29, v30, v31
	s_nop 1
	v_mov_b32_dpp v30, v29 quad_perm:[2,3,0,1] row_mask:0xf bank_mask:0xf
	s_waitcnt lgkmcnt(0)
	v_add_f32_e32 v32, v48, v49
	v_fmamk_f32 v32, v32, 0x3c000000, v244
	v_rsq_f32_e32 v32, v32
	v_add_f32_e32 v29, v29, v30
	s_nop 1
	v_mov_b32_dpp v30, v29 row_half_mirror row_mask:0xf bank_mask:0xf
	v_mul_f32_e32 v31, v44, v32
	v_mul_f32_e32 v31, v23, v31
	v_cvt_pk_bf16_f32 v31, v31, s0
	ds_write_b16 v6, v31 offset:2816
	v_add_f32_e32 v29, v29, v30
	s_nop 1
	v_mov_b32_dpp v30, v29 row_mirror row_mask:0xf bank_mask:0xf
	v_mul_f32_e32 v31, v45, v32
	v_mul_f32_e32 v31, v22, v31
	v_cvt_pk_bf16_f32 v31, v31, s0
	ds_write_b16 v6, v31 offset:2880
	v_add_f32_e32 v29, v29, v30
	v_mul_f32_e32 v31, v46, v32
	ds_swizzle_b32 v33, v29 offset:swizzle(SWAP,16)
	v_mul_f32_e32 v31, v17, v31
	v_mul_f32_e32 v30, v47, v32
	v_cvt_pk_bf16_f32 v31, v31, s0
	v_mul_f32_e32 v30, v16, v30
	ds_write_b16 v6, v31 offset:2944
	v_cvt_pk_bf16_f32 v44, v30, s0
	ds_read2_b32 v[30:31], v43 offset0:128 offset1:160
	s_waitcnt lgkmcnt(2)
	v_add_f32_e32 v29, v29, v33
	ds_read2_b32 v[32:33], v43 offset0:192 offset1:224
	v_fmamk_f32 v29, v29, 0x3c000000, v244
	v_rsq_f32_e32 v29, v29
	s_waitcnt lgkmcnt(1)
	v_sub_f32_e32 v40, v40, v31
	v_sub_f32_e32 v39, v39, v30
	v_mul_f32_e32 v30, v40, v40
	v_fmac_f32_e32 v30, v39, v39
	s_waitcnt lgkmcnt(0)
	v_sub_f32_e32 v38, v38, v32
	v_fmac_f32_e32 v30, v38, v38
	v_sub_f32_e32 v37, v37, v33
	v_fmac_f32_e32 v30, v37, v37
	s_nop 1
	v_mov_b32_dpp v31, v30 quad_perm:[1,0,3,2] row_mask:0xf bank_mask:0xf
	v_mul_f32_e32 v32, v50, v29
	v_mul_f32_e32 v32, v23, v32
	v_cvt_pk_bf16_f32 v32, v32, s0
	ds_write_b16 v6, v32 offset:4096
	v_add_f32_e32 v30, v30, v31
	s_nop 1
	v_mov_b32_dpp v31, v30 quad_perm:[2,3,0,1] row_mask:0xf bank_mask:0xf
	v_mul_f32_e32 v32, v51, v29
	v_mul_f32_e32 v32, v22, v32
	v_cvt_pk_bf16_f32 v32, v32, s0
	ds_write_b16 v6, v32 offset:4160
	v_add_f32_e32 v30, v30, v31
	s_nop 1
	v_mov_b32_dpp v31, v30 row_half_mirror row_mask:0xf bank_mask:0xf
	v_mul_f32_e32 v32, v42, v29
	v_add_u32_e32 v43, 0x2400, v15
	v_mul_f32_e32 v32, v17, v32
	v_cvt_pk_bf16_f32 v32, v32, s0
	v_add_f32_e32 v33, v30, v31
	s_nop 1
	v_mov_b32_dpp v42, v33 row_mirror row_mask:0xf bank_mask:0xf
	ds_read2_b32 v[30:31], v43 offset1:32
	ds_write_b16 v6, v32 offset:4224
	v_mul_f32_e32 v29, v41, v29
	v_mul_f32_e32 v29, v16, v29
	v_add_f32_e32 v41, v33, v42
	ds_read2_b32 v[32:33], v43 offset0:64 offset1:96
	s_waitcnt lgkmcnt(2)
	v_sub_f32_e32 v36, v36, v31
	v_sub_f32_e32 v35, v35, v30
	v_mul_f32_e32 v30, v36, v36
	v_fmac_f32_e32 v30, v35, v35
	s_waitcnt lgkmcnt(0)
	v_sub_f32_e32 v32, v34, v32
	v_fmac_f32_e32 v30, v32, v32
	v_sub_f32_e32 v33, v28, v33
	v_fmac_f32_e32 v30, v33, v33
	s_nop 1
	v_mov_b32_dpp v28, v30 quad_perm:[1,0,3,2] row_mask:0xf bank_mask:0xf
	ds_swizzle_b32 v42, v41 offset:swizzle(SWAP,16)
	v_cvt_pk_bf16_f32 v29, v29, s0
	ds_write_b16 v6, v29 offset:4288
	ds_write_b16 v6, v44 offset:3008
	v_add_f32_e32 v28, v30, v28
	s_nop 1
	v_mov_b32_dpp v30, v28 quad_perm:[2,3,0,1] row_mask:0xf bank_mask:0xf
	s_waitcnt lgkmcnt(2)
	v_add_f32_e32 v31, v41, v42
	v_fmamk_f32 v31, v31, 0x3c000000, v244
	v_rsq_f32_e32 v31, v31
	v_add_f32_e32 v28, v28, v30
	s_nop 1
	v_mov_b32_dpp v30, v28 row_half_mirror row_mask:0xf bank_mask:0xf
	v_mul_f32_e32 v29, v39, v31
	v_mul_f32_e32 v29, v23, v29
	v_cvt_pk_bf16_f32 v29, v29, s0
	ds_write_b16 v6, v29 offset:4352
	v_add_f32_e32 v28, v28, v30
	s_nop 1
	v_mov_b32_dpp v30, v28 row_mirror row_mask:0xf bank_mask:0xf
	v_mul_f32_e32 v29, v40, v31
	v_mul_f32_e32 v29, v22, v29
	v_cvt_pk_bf16_f32 v29, v29, s0
	ds_write_b16 v6, v29 offset:4416
	v_add_f32_e32 v30, v28, v30
	ds_swizzle_b32 v34, v30 offset:swizzle(SWAP,16)
	v_mul_f32_e32 v29, v38, v31
	v_mul_f32_e32 v29, v17, v29
	v_cvt_pk_bf16_f32 v28, v29, s0
	ds_write_b16 v6, v28 offset:4480
	ds_read2_b32 v[28:29], v43 offset0:128 offset1:160
	s_waitcnt lgkmcnt(2)
	v_add_f32_e32 v30, v30, v34
	v_fmamk_f32 v30, v30, 0x3c000000, v244
	v_mul_f32_e32 v37, v37, v31
	v_rsq_f32_e32 v34, v30
	ds_read2_b32 v[30:31], v43 offset0:192 offset1:224
	s_waitcnt lgkmcnt(1)
	v_sub_f32_e32 v29, v27, v29
	v_sub_f32_e32 v28, v26, v28
	v_mul_f32_e32 v26, v29, v29
	v_fmac_f32_e32 v26, v28, v28
	s_waitcnt lgkmcnt(0)
	v_sub_f32_e32 v30, v25, v30
	v_fmac_f32_e32 v26, v30, v30
	v_sub_f32_e32 v31, v24, v31
	v_fmac_f32_e32 v26, v31, v31
	s_nop 1
	v_mov_b32_dpp v24, v26 quad_perm:[1,0,3,2] row_mask:0xf bank_mask:0xf
	v_mul_f32_e32 v25, v16, v37
	v_cvt_pk_bf16_f32 v25, v25, s0
	ds_write_b16 v6, v25 offset:4544
	v_mul_f32_e32 v25, v35, v34
	v_add_f32_e32 v24, v26, v24
	s_nop 1
	v_mov_b32_dpp v26, v24 quad_perm:[2,3,0,1] row_mask:0xf bank_mask:0xf
	v_mul_f32_e32 v25, v23, v25
	v_cvt_pk_bf16_f32 v25, v25, s0
	ds_write_b16 v6, v25 offset:4608
	v_mul_f32_e32 v25, v36, v34
	v_add_f32_e32 v24, v24, v26
	s_nop 1
	v_mov_b32_dpp v26, v24 row_half_mirror row_mask:0xf bank_mask:0xf
	v_mul_f32_e32 v25, v22, v25
	v_cvt_pk_bf16_f32 v25, v25, s0
	ds_write_b16 v6, v25 offset:4672
	v_mul_f32_e32 v25, v32, v34
	v_add_f32_e32 v24, v24, v26
	s_nop 1
	v_mov_b32_dpp v26, v24 row_mirror row_mask:0xf bank_mask:0xf
	v_mul_f32_e32 v25, v17, v25
	v_cvt_pk_bf16_f32 v25, v25, s0
	ds_write_b16 v6, v25 offset:4736
	v_mul_f32_e32 v25, v33, v34
	v_add_f32_e32 v26, v24, v26
	ds_swizzle_b32 v27, v26 offset:swizzle(SWAP,16)
	v_mul_f32_e32 v24, v16, v25
	v_add_u32_e32 v33, 0x3000, v15
	v_cvt_pk_bf16_f32 v32, v24, s0
	ds_read2_b32 v[24:25], v33 offset1:32
	s_waitcnt lgkmcnt(1)
	v_add_f32_e32 v26, v26, v27
	v_fmamk_f32 v26, v26, 0x3c000000, v244
	v_rsq_f32_e32 v34, v26
	ds_read2_b32 v[26:27], v33 offset0:64 offset1:96
	s_waitcnt lgkmcnt(1)
	v_sub_f32_e32 v25, v21, v25
	v_sub_f32_e32 v24, v18, v24
	v_mul_f32_e32 v18, v25, v25
	v_fmac_f32_e32 v18, v24, v24
	s_waitcnt lgkmcnt(0)
	v_sub_f32_e32 v26, v20, v26
	v_fmac_f32_e32 v18, v26, v26
	v_sub_f32_e32 v27, v19, v27
	v_fmac_f32_e32 v18, v27, v27
	s_nop 1
	v_mov_b32_dpp v19, v18 quad_perm:[1,0,3,2] row_mask:0xf bank_mask:0xf
	v_mul_f32_e32 v20, v28, v34
	v_mul_f32_e32 v20, v23, v20
	v_cvt_pk_bf16_f32 v20, v20, s0
	ds_write_b16 v6, v20 offset:4864
	v_add_f32_e32 v18, v18, v19
	s_nop 1
	v_mov_b32_dpp v19, v18 quad_perm:[2,3,0,1] row_mask:0xf bank_mask:0xf
	v_mul_f32_e32 v20, v29, v34
	v_mul_f32_e32 v20, v22, v20
	v_cvt_pk_bf16_f32 v20, v20, s0
	ds_write_b16 v6, v20 offset:4928
	v_add_f32_e32 v18, v18, v19
	s_nop 1
	v_mov_b32_dpp v19, v18 row_half_mirror row_mask:0xf bank_mask:0xf
	v_mul_f32_e32 v20, v30, v34
	v_mul_f32_e32 v20, v17, v20
	v_cvt_pk_bf16_f32 v20, v20, s0
	ds_write_b16 v6, v20 offset:4992
	v_add_f32_e32 v21, v18, v19
	s_nop 1
	v_mov_b32_dpp v28, v21 row_mirror row_mask:0xf bank_mask:0xf
	ds_read2_b32 v[18:19], v33 offset0:128 offset1:160
	v_mul_f32_e32 v20, v31, v34
	v_mul_f32_e32 v29, v16, v20
	ds_write_b16 v6, v32 offset:4800
	v_add_f32_e32 v28, v21, v28
	ds_read2_b32 v[20:21], v33 offset0:192 offset1:224
	s_waitcnt lgkmcnt(2)
	v_sub_f32_e32 v11, v11, v18
	v_sub_f32_e32 v18, v14, v19
	v_mul_f32_e32 v14, v18, v18
	v_fmac_f32_e32 v14, v11, v11
	s_waitcnt lgkmcnt(0)
	v_sub_f32_e32 v19, v13, v20
	v_fmac_f32_e32 v14, v19, v19
	v_sub_f32_e32 v20, v12, v21
	v_fmac_f32_e32 v14, v20, v20
	s_nop 1
	v_mov_b32_dpp v12, v14 quad_perm:[1,0,3,2] row_mask:0xf bank_mask:0xf
	ds_swizzle_b32 v30, v28 offset:swizzle(SWAP,16)
	v_cvt_pk_bf16_f32 v13, v29, s0
	ds_write_b16 v6, v13 offset:5056
	v_add_f32_e32 v12, v14, v12
	s_nop 1
	v_mov_b32_dpp v14, v12 quad_perm:[2,3,0,1] row_mask:0xf bank_mask:0xf
	s_waitcnt lgkmcnt(1)
	v_add_f32_e32 v21, v28, v30
	v_fmamk_f32 v21, v21, 0x3c000000, v244
	v_rsq_f32_e32 v21, v21
	v_add_f32_e32 v12, v12, v14
	s_nop 1
	v_mov_b32_dpp v14, v12 row_half_mirror row_mask:0xf bank_mask:0xf
	v_mul_f32_e32 v13, v24, v21
	v_mul_f32_e32 v13, v23, v13
	v_cvt_pk_bf16_f32 v13, v13, s0
	ds_write_b16 v6, v13 offset:6144
	v_add_f32_e32 v12, v12, v14
	s_nop 1
	v_mov_b32_dpp v14, v12 row_mirror row_mask:0xf bank_mask:0xf
	v_mul_f32_e32 v13, v25, v21
	v_mul_f32_e32 v13, v22, v13
	v_cvt_pk_bf16_f32 v13, v13, s0
	ds_write_b16 v6, v13 offset:6208
	v_add_f32_e32 v14, v12, v14
	ds_swizzle_b32 v24, v14 offset:swizzle(SWAP,16)
	v_mul_f32_e32 v13, v26, v21
	v_mul_f32_e32 v13, v17, v13
	v_cvt_pk_bf16_f32 v13, v13, s0
	v_add_u32_e32 v25, 0x3400, v15
	ds_write_b16 v6, v13 offset:6272
	ds_read2_b32 v[12:13], v25 offset1:32
	s_waitcnt lgkmcnt(2)
	v_add_f32_e32 v14, v14, v24
	v_fmamk_f32 v14, v14, 0x3c000000, v244
	v_rsq_f32_e32 v24, v14
	ds_read2_b32 v[14:15], v25 offset0:64 offset1:96
	s_waitcnt lgkmcnt(1)
	v_sub_f32_e32 v7, v7, v12
	v_sub_f32_e32 v12, v10, v13
	v_mul_f32_e32 v10, v12, v12
	v_fmac_f32_e32 v10, v7, v7
	s_waitcnt lgkmcnt(0)
	v_sub_f32_e32 v13, v9, v14
	v_fmac_f32_e32 v10, v13, v13
	v_sub_f32_e32 v14, v8, v15
	v_fmac_f32_e32 v10, v14, v14
	s_nop 1
	v_mov_b32_dpp v8, v10 quad_perm:[1,0,3,2] row_mask:0xf bank_mask:0xf
	v_mul_f32_e32 v21, v27, v21
	v_mul_f32_e32 v9, v16, v21
	v_cvt_pk_bf16_f32 v9, v9, s0
	ds_write_b16 v6, v9 offset:6336
	v_add_f32_e32 v8, v10, v8
	s_nop 1
	v_mov_b32_dpp v10, v8 quad_perm:[2,3,0,1] row_mask:0xf bank_mask:0xf
	v_mul_f32_e32 v9, v11, v24
	v_mul_f32_e32 v9, v23, v9
	v_cvt_pk_bf16_f32 v9, v9, s0
	ds_write_b16 v6, v9 offset:6400
	v_add_f32_e32 v8, v8, v10
	s_nop 1
	v_mov_b32_dpp v10, v8 row_half_mirror row_mask:0xf bank_mask:0xf
	v_mul_f32_e32 v9, v18, v24
	v_mul_f32_e32 v9, v22, v9
	v_cvt_pk_bf16_f32 v9, v9, s0
	ds_write_b16 v6, v9 offset:6464
	v_add_f32_e32 v10, v8, v10
	s_nop 1
	v_mov_b32_dpp v11, v10 row_mirror row_mask:0xf bank_mask:0xf
	v_mul_f32_e32 v9, v19, v24
	v_mul_f32_e32 v8, v17, v9
	v_cvt_pk_bf16_f32 v15, v8, s0
	ds_read2_b32 v[8:9], v25 offset0:128 offset1:160
	ds_write_b16 v6, v15 offset:6528
	v_add_f32_e32 v15, v10, v11
	ds_read2_b32 v[10:11], v25 offset0:192 offset1:224
	ds_swizzle_b32 v18, v15 offset:swizzle(SWAP,16)
	s_waitcnt lgkmcnt(3)
	v_sub_f32_e32 v5, v5, v9
	v_sub_f32_e32 v4, v4, v8
	v_mul_f32_e32 v8, v5, v5
	v_fmac_f32_e32 v8, v4, v4
	s_waitcnt lgkmcnt(1)
	v_sub_f32_e32 v3, v3, v10
	v_fmac_f32_e32 v8, v3, v3
	v_sub_f32_e32 v2, v2, v11
	v_fmac_f32_e32 v8, v2, v2
	s_nop 1
	v_mov_b32_dpp v9, v8 quad_perm:[1,0,3,2] row_mask:0xf bank_mask:0xf
	s_waitcnt lgkmcnt(0)
	v_add_f32_e32 v11, v15, v18
	v_fmamk_f32 v11, v11, 0x3c000000, v244
	v_rsq_f32_e32 v11, v11
	v_mul_f32_e32 v10, v20, v24
	v_add_f32_e32 v8, v8, v9
	s_nop 1
	v_mov_b32_dpp v9, v8 quad_perm:[2,3,0,1] row_mask:0xf bank_mask:0xf
	v_mul_f32_e32 v7, v7, v11
	v_mul_f32_e32 v7, v23, v7
	v_cvt_pk_bf16_f32 v7, v7, s0
	ds_write_b16 v6, v7 offset:6656
	v_add_f32_e32 v8, v8, v9
	s_nop 1
	v_mov_b32_dpp v9, v8 row_half_mirror row_mask:0xf bank_mask:0xf
	v_mul_f32_e32 v7, v12, v11
	v_mul_f32_e32 v7, v22, v7
	v_cvt_pk_bf16_f32 v7, v7, s0
	ds_write_b16 v6, v7 offset:6720
	v_add_f32_e32 v8, v8, v9
	s_nop 1
	v_mov_b32_dpp v9, v8 row_mirror row_mask:0xf bank_mask:0xf
	v_mul_f32_e32 v7, v13, v11
	v_mul_f32_e32 v7, v17, v7
	v_cvt_pk_bf16_f32 v7, v7, s0
	ds_write_b16 v6, v7 offset:6784
	v_add_f32_e32 v8, v8, v9
	ds_swizzle_b32 v9, v8 offset:swizzle(SWAP,16)
	v_mul_f32_e32 v7, v14, v11
	v_mul_f32_e32 v10, v16, v10
	v_mul_f32_e32 v7, v16, v7
	v_cvt_pk_bf16_f32 v10, v10, s0
	s_waitcnt lgkmcnt(0)
	v_add_f32_e32 v8, v8, v9
	v_fmamk_f32 v8, v8, 0x3c000000, v244
	v_rsq_f32_e32 v8, v8
	v_cvt_pk_bf16_f32 v7, v7, s0
	ds_write_b16 v6, v10 offset:6592
	ds_write_b16 v6, v7 offset:6848
	v_mul_f32_e32 v4, v4, v8
	v_mul_f32_e32 v4, v23, v4
	v_mul_f32_e32 v2, v2, v8
	v_cvt_pk_bf16_f32 v4, v4, s0
	v_mul_f32_e32 v2, v16, v2
	ds_write_b16 v6, v4 offset:6912
	v_mul_f32_e32 v4, v5, v8
	v_mul_f32_e32 v3, v3, v8
	v_cvt_pk_bf16_f32 v2, v2, s0
	v_mul_f32_e32 v4, v22, v4
	v_mul_f32_e32 v3, v17, v3
	ds_write_b16 v6, v2 offset:7104
	v_lshlrev_b32_e32 v2, 4, v66
	v_cvt_pk_bf16_f32 v4, v4, s0
	v_cvt_pk_bf16_f32 v3, v3, s0
	v_and_b32_e32 v230, 0xf0, v2
	ds_write_b16 v6, v4 offset:6976
	ds_write_b16 v6, v3 offset:7040
	v_ashrrev_i32_e32 v10, 4, v66
	v_add_u32_e32 v18, s0, v230
	s_waitcnt lgkmcnt(0)
	v_lshl_add_u32 v2, v10, 8, v18
	v_ashrrev_i32_e32 v11, 31, v10
	v_lshl_add_u64 v[12:13], s[4:5], 0, v[230:231]
	ds_read_b128 v[2:5], v2
	v_lshlrev_b64 v[6:7], 11, v[10:11]
	v_add_u32_e32 v16, 4, v10
	v_lshl_add_u64 v[14:15], v[12:13], 0, v[6:7]
	v_lshl_add_u32 v6, v16, 8, v18
	ds_read_b128 v[6:9], v6
	v_ashrrev_i32_e32 v17, 31, v16
	s_waitcnt lgkmcnt(1)
	global_store_dwordx4 v[14:15], v[2:5], off offset:1024 nt
	s_nop 1
	v_lshlrev_b64 v[2:3], 11, v[16:17]
	v_lshl_add_u64 v[2:3], v[12:13], 0, v[2:3]
	s_waitcnt lgkmcnt(0)
	global_store_dwordx4 v[2:3], v[6:9], off offset:1024 nt
	v_add_u32_e32 v16, 12, v10
	v_ashrrev_i32_e32 v17, 31, v16
	v_add_u32_e32 v6, 8, v10
	v_lshl_add_u32 v2, v6, 8, v18
	v_ashrrev_i32_e32 v7, 31, v6
	ds_read_b128 v[2:5], v2
	v_lshlrev_b64 v[6:7], 11, v[6:7]
	v_lshl_add_u64 v[14:15], v[12:13], 0, v[6:7]
	v_lshl_add_u32 v6, v16, 8, v18
	ds_read_b128 v[6:9], v6
	s_waitcnt lgkmcnt(1)
	global_store_dwordx4 v[14:15], v[2:5], off offset:1024 nt
	s_nop 1
	v_lshlrev_b64 v[2:3], 11, v[16:17]
	v_lshl_add_u64 v[2:3], v[12:13], 0, v[2:3]
	s_waitcnt lgkmcnt(0)
	global_store_dwordx4 v[2:3], v[6:9], off offset:1024 nt
	v_add_u32_e32 v16, 20, v10
	v_ashrrev_i32_e32 v17, 31, v16
	v_add_u32_e32 v6, 16, v10
	v_lshl_add_u32 v2, v6, 8, v18
	v_ashrrev_i32_e32 v7, 31, v6
	ds_read_b128 v[2:5], v2
	v_lshlrev_b64 v[6:7], 11, v[6:7]
	v_lshl_add_u64 v[14:15], v[12:13], 0, v[6:7]
	v_lshl_add_u32 v6, v16, 8, v18
	ds_read_b128 v[6:9], v6
	s_waitcnt lgkmcnt(1)
	global_store_dwordx4 v[14:15], v[2:5], off offset:1024 nt
	s_nop 1
	v_lshlrev_b64 v[2:3], 11, v[16:17]
	v_lshl_add_u64 v[2:3], v[12:13], 0, v[2:3]
	s_waitcnt lgkmcnt(0)
	global_store_dwordx4 v[2:3], v[6:9], off offset:1024 nt
	s_nop 1
	v_add_u32_e32 v6, 24, v10
	v_lshl_add_u32 v2, v6, 8, v18
	v_ashrrev_i32_e32 v7, 31, v6
	ds_read_b128 v[2:5], v2
	v_lshlrev_b64 v[6:7], 11, v[6:7]
	v_add_u32_e32 v10, 28, v10
	v_lshl_add_u64 v[14:15], v[12:13], 0, v[6:7]
	v_lshl_add_u32 v6, v10, 8, v18
	ds_read_b128 v[6:9], v6
	v_ashrrev_i32_e32 v11, 31, v10
	s_waitcnt lgkmcnt(1)
	global_store_dwordx4 v[14:15], v[2:5], off offset:1024 nt
	s_nop 1
	v_lshlrev_b64 v[2:3], 11, v[10:11]
	v_lshl_add_u64 v[2:3], v[12:13], 0, v[2:3]
	s_waitcnt lgkmcnt(0)
	global_store_dwordx4 v[2:3], v[6:9], off offset:1024 nt
	s_branch .LBB0_1312
